# v31 + SB attention output stores widened: permlane32_swap pairs, 8 dwordx4 instead of 16 dwordx2
# speedup vs baseline: 1.0141x; 1.0032x over previous
; __device__ __forceinline__ unsigned cvtpk(float lo, float hi) { f32x2_t v = {lo, hi}; bf16x2_t b = __builtin_convertvector(v, bf16x2_t); return __builtin_bit_cast(unsigned, b); }
; __device__ __forceinline__ void sb_attn(const bf16* QKV, bf16* O, LAS unsigned char* lds, int tid) {
;     ...
;         { bf16* op = O + (tok0 + qr0 + l32) * D + h * 64 + 4 * hi;
; #pragma unroll
;           for (int g = 0; g < 4; ++g) {
;               const u32x2 a = {cvtpk(o0[4 * g], o0[4 * g + 1]), cvtpk(o0[4 * g + 2], o0[4 * g + 3])}, c = {cvtpk(o1[4 * g], o1[4 * g + 1]), cvtpk(o1[4 * g + 2], o1[4 * g + 3])};
;               *(u32x2*)(op + 8 * g) = a; *(u32x2*)(op + 32 + 8 * g) = c; } }
.LBB0_192:
	s_ashr_i32 s7, s6, 31
	s_lshl_b64 s[6:7], s[6:7], 12
	s_or_b32 s6, s6, s11
	v_mov_b32_e32 v33, s7
	v_or_b32_e32 v32, s6, v96
	v_lshlrev_b64 v[32:33], 11, v[32:33]
	v_lshl_add_u64 v[32:33], s[92:93], 0, v[32:33]
	s_lshl_b32 s88, s10, 7
	v_lshl_add_u64 v[32:33], v[32:33], 0, s[88:89]
	v_mov_b32_e32 v107, v157
	v_lshl_add_u64 v[32:33], v[32:33], 0, v[106:107]
	v_lshl_add_u64 v[32:33], v[32:33], 0, v[106:107]
	v_cvt_pk_bf16_f32 v16, v16, v17
	v_cvt_pk_bf16_f32 v17, v18, v19
	v_cvt_pk_bf16_f32 v18, v20, v21
	v_cvt_pk_bf16_f32 v19, v22, v23
	v_cvt_pk_bf16_f32 v20, v24, v25
	v_cvt_pk_bf16_f32 v21, v26, v27
	v_cvt_pk_bf16_f32 v22, v28, v29
	v_cvt_pk_bf16_f32 v23, v30, v31
	v_cvt_pk_bf16_f32 v0, v0, v1
	v_cvt_pk_bf16_f32 v1, v2, v3
	v_cvt_pk_bf16_f32 v2, v4, v5
	v_cvt_pk_bf16_f32 v3, v6, v7
	v_cvt_pk_bf16_f32 v4, v8, v9
	v_cvt_pk_bf16_f32 v5, v10, v11
	v_cvt_pk_bf16_f32 v6, v12, v13
	v_cvt_pk_bf16_f32 v7, v14, v15
	s_add_i32 s8, s8, s67
	s_add_i32 s9, s9, s67
	s_nop 1
	v_permlane32_swap_b32_e32 v16, v18
	v_permlane32_swap_b32_e32 v17, v19
	v_permlane32_swap_b32_e32 v20, v22
	v_permlane32_swap_b32_e32 v21, v23
	v_permlane32_swap_b32_e32 v0, v2
	v_permlane32_swap_b32_e32 v1, v3
	v_permlane32_swap_b32_e32 v4, v6
	v_permlane32_swap_b32_e32 v5, v7
	s_cmpk_gt_i32 s8, 0x3fff
	global_store_dwordx4 v[32:33], v[16:19], off
	global_store_dwordx4 v[32:33], v[20:23], off offset:32
	global_store_dwordx4 v[32:33], v[0:3], off offset:64
	global_store_dwordx4 v[32:33], v[4:7], off offset:96
	s_cbranch_scc1 .LBB0_200
